# weight transpose read-back: the 32 strided LDS reads per tile are issued in groups of 16/8 with counted lgkmcnt waits instead of 16 read-pair/wait round trips
# baseline (speedup 1.0000x reference)
.LBB0_569:
	v_cvt_f32_u32_e32 v33, s35
	s_sub_i32 s4, 0, s35
	s_abs_i32 s1, s34
	s_ashr_i32 s0, s34, 31
	v_rcp_iflag_f32_e32 v33, v33
	s_nop 0
	v_mul_f32_e32 v33, 0x4f7ffffe, v33
	v_cvt_u32_f32_e32 v33, v33
	s_nop 0
	v_readfirstlane_b32 s5, v33
	s_mul_i32 s4, s4, s5
	s_mul_hi_u32 s4, s5, s4
	s_add_i32 s5, s5, s4
	s_mul_hi_u32 s4, s1, s5
	s_mul_i32 s5, s4, s35
	s_sub_i32 s1, s1, s5
	s_add_i32 s5, s4, 1
	s_sub_i32 s36, s1, s35
	s_cmp_ge_u32 s1, s35
	s_cselect_b32 s4, s5, s4
	s_cselect_b32 s1, s36, s1
	s_add_i32 s5, s4, 1
	s_cmp_ge_u32 s1, s35
	s_cselect_b32 s1, s5, s4
	s_xor_b32 s1, s1, s0
	s_sub_i32 s1, s1, s0
	s_lshl_b32 s4, s1, 6
	s_ashr_i32 s5, s4, 31
	s_lshl_b64 s[4:5], s[4:5], 1
	v_lshl_add_u64 v[34:35], v[34:35], 0, s[4:5]
	v_mov_b32_e32 v33, v145
	v_lshl_add_u64 v[34:35], v[34:35], 0, v[32:33]
	ds_read_b32 v100, v37
	ds_read_b32 v101, v37 offset:1028
	ds_read_b32 v102, v37 offset:2056
	ds_read_b32 v103, v37 offset:3084
	ds_read_b32 v104, v37 offset:4112
	ds_read_b32 v105, v37 offset:5140
	ds_read_b32 v106, v37 offset:6168
	ds_read_b32 v107, v37 offset:7196
	ds_read_b32 v112, v46
	ds_read_b32 v113, v46 offset:1028
	ds_read_b32 v114, v46 offset:2056
	ds_read_b32 v115, v46 offset:3084
	ds_read_b32 v116, v46 offset:4112
	ds_read_b32 v117, v46 offset:5140
	ds_read_b32 v118, v46 offset:6168
	ds_read_b32 v119, v46 offset:7196
	s_mul_i32 s0, s1, s35
	s_sub_i32 s0, s34, s0
	s_lshl_b32 s0, s0, 8
	s_waitcnt lgkmcnt(8)
	v_cvt_pk_bf16_f32 v60, v100, v101
	v_cvt_pk_bf16_f32 v61, v102, v103
	v_cvt_pk_bf16_f32 v62, v104, v105
	v_cvt_pk_bf16_f32 v63, v106, v107
	v_add_u32_e32 v33, s0, v36
	v_mad_i64_i32 v[64:65], s[4:5], v33, s70, v[34:35]
	global_store_dwordx4 v[64:65], v[60:63], off
	ds_read_b32 v100, v48
	ds_read_b32 v101, v48 offset:1028
	ds_read_b32 v102, v48 offset:2056
	ds_read_b32 v103, v48 offset:3084
	ds_read_b32 v104, v48 offset:4112
	ds_read_b32 v105, v48 offset:5140
	ds_read_b32 v106, v48 offset:6168
	ds_read_b32 v107, v48 offset:7196
	s_waitcnt lgkmcnt(8)
	v_cvt_pk_bf16_f32 v108, v112, v113
	v_cvt_pk_bf16_f32 v109, v114, v115
	v_cvt_pk_bf16_f32 v110, v116, v117
	v_cvt_pk_bf16_f32 v111, v118, v119
	v_add_u32_e32 v33, s0, v45
	v_mad_i64_i32 v[64:65], s[4:5], v33, s70, v[34:35]
	global_store_dwordx4 v[64:65], v[108:111], off
	ds_read_b32 v112, v50
	ds_read_b32 v113, v50 offset:1028
	ds_read_b32 v114, v50 offset:2056
	ds_read_b32 v115, v50 offset:3084
	ds_read_b32 v116, v50 offset:4112
	ds_read_b32 v117, v50 offset:5140
	ds_read_b32 v118, v50 offset:6168
	ds_read_b32 v119, v50 offset:7196
	s_waitcnt lgkmcnt(8)
	v_cvt_pk_bf16_f32 v60, v100, v101
	v_cvt_pk_bf16_f32 v61, v102, v103
	v_cvt_pk_bf16_f32 v62, v104, v105
	v_cvt_pk_bf16_f32 v63, v106, v107
	v_add_u32_e32 v33, s0, v47
	v_mad_i64_i32 v[64:65], s[4:5], v33, s70, v[34:35]
	global_store_dwordx4 v[64:65], v[60:63], off
	s_waitcnt lgkmcnt(0)
	v_cvt_pk_bf16_f32 v108, v112, v113
	v_cvt_pk_bf16_f32 v109, v114, v115
	v_cvt_pk_bf16_f32 v110, v116, v117
	v_cvt_pk_bf16_f32 v111, v118, v119
	v_add_u32_e32 v33, s0, v49
	v_mad_i64_i32 v[34:35], s[0:1], v33, s70, v[34:35]
	s_add_i32 s7, s7, s55
	s_add_i32 s6, s6, s55
	s_add_i32 s10, s10, s55
	s_add_i32 s9, s9, s55
	s_add_i32 s11, s11, s55
	s_add_i32 s13, s13, s55
	s_add_i32 s12, s12, s55
	s_add_i32 s14, s14, s55
	s_add_i32 s0, s54, s7
	s_cmp_ge_i32 s0, s8
	global_store_dwordx4 v[34:35], v[108:111], off
	s_barrier
	s_cbranch_scc1 .LBB0_9
